# w_k transposes also moved from after the A-out unit into the A-in tail (workgroups 128..255)
# speedup vs baseline: 1.0214x; 1.0066x over previous
.LBB0_354:
	s_mov_b32 s98, 1
	s_mov_b32 s70, 0x2c00
	s_mov_b32 s71, 0x3800
	s_mov_b32 s72, 0x800
	s_mov_b32 s73, 0x0
	s_mov_b32 s74, 0x0
	s_mov_b32 s75, 0x37ff
	s_lshl_b32 s76, s70, 5
	s_lshl_b32 s77, s70, 7
	s_lshl_b32 s78, s70, 6
	s_lshl_b32 s79, s70, 1
	s_branch .Lp0_entry
